# v61 + gla_pass operand prefetch (both passes): per-row 64-bit v_mad_i64_i32 address recomputation replaced by one row-0 address and v_lshl_add_u64 stride steps (28 fewer v_mad_i64, 13 fewer v_or per i
# baseline (speedup 1.0000x reference)
.LBB0_237:
	s_or_b64 exec, exec, s[8:9]
	s_lshr_b32 s36, s19, 2
	v_lshl_or_b32 v0, s36, 7, v32
	v_add_u32_e32 v88, s1, v47
	v_lshl_add_u64 v[84:85], s[10:11], 0, v[0:1]
	s_mov_b32 s100, s90
	s_mov_b32 s101, 0
	v_mad_i64_i32 v[112:113], s[8:9], v88, s90, v[84:85]
	s_lshl_b32 s36, s36, 8
	v_lshl_add_u64 v[100:101], v[34:35], 0, s[36:37]
	v_mad_i64_i32 v[114:115], s[8:9], v88, s90, v[100:101]
	global_load_ushort v77, v[112:113], off offset:1024
	v_lshl_add_u64 v[112:113], v[112:113], 0, s[100:101]
	global_load_ushort v78, v[112:113], off offset:1024
	v_lshl_add_u64 v[112:113], v[112:113], 0, s[100:101]
	global_load_ushort v79, v[112:113], off offset:1024
	v_lshl_add_u64 v[112:113], v[112:113], 0, s[100:101]
	global_load_ushort v80, v[112:113], off offset:1024
	v_lshl_add_u64 v[112:113], v[112:113], 0, s[100:101]
	global_load_ushort v81, v[112:113], off offset:1024
	v_lshl_add_u64 v[112:113], v[112:113], 0, s[100:101]
	global_load_ushort v82, v[112:113], off offset:1024
	v_lshl_add_u64 v[112:113], v[112:113], 0, s[100:101]
	global_load_ushort v83, v[112:113], off offset:1024
	v_lshl_add_u64 v[112:113], v[112:113], 0, s[100:101]
	global_load_ushort v84, v[112:113], off offset:1024
	global_load_dword v85, v[114:115], off offset:1536
	v_lshl_add_u64 v[114:115], v[114:115], 0, s[100:101]
	global_load_dword v86, v[114:115], off offset:1536
	v_lshl_add_u64 v[114:115], v[114:115], 0, s[100:101]
	global_load_dword v87, v[114:115], off offset:1536
	v_lshl_add_u64 v[114:115], v[114:115], 0, s[100:101]
	global_load_dword v88, v[114:115], off offset:1536
	v_lshl_add_u64 v[114:115], v[114:115], 0, s[100:101]
	global_load_dword v89, v[114:115], off offset:1536
	v_lshl_add_u64 v[114:115], v[114:115], 0, s[100:101]
	global_load_dword v90, v[114:115], off offset:1536
	v_lshl_add_u64 v[114:115], v[114:115], 0, s[100:101]
	global_load_dword v91, v[114:115], off offset:1536
	v_lshl_add_u64 v[114:115], v[114:115], 0, s[100:101]
	global_load_dword v92, v[114:115], off offset:1536

.LBB0_383:
	s_or_b64 exec, exec, s[8:9]
	s_lshr_b32 s36, s4, 2
	s_lshl_b32 s8, s36, 6
	v_add_u32_e32 v78, s1, v89
	v_or_b32_e32 v70, s8, v87
	v_mov_b64_e32 v[72:73], s[26:27]
	v_add_lshl_u32 v0, v149, s8, 1
	v_lshl_or_b32 v70, v70, 1, v237
	v_mov_b32_e32 v71, v1
	s_mov_b32 s100, s90
	s_mov_b32 s101, 0
	v_mad_i64_i32 v[74:75], s[8:9], v78, s90, v[72:73]
	v_lshl_add_u64 v[76:77], v[74:75], 0, v[0:1]
	v_lshl_add_u64 v[74:75], v[74:75], 0, v[70:71]
	global_load_ushort v194, v[76:77], off
	global_load_ushort v197, v[74:75], off
	v_lshl_add_u64 v[76:77], v[76:77], 0, s[100:101]
	v_lshl_add_u64 v[74:75], v[74:75], 0, s[100:101]
	global_load_ushort v195, v[76:77], off
	global_load_ushort v199, v[74:75], off
	v_lshl_add_u64 v[76:77], v[76:77], 0, s[100:101]
	v_lshl_add_u64 v[74:75], v[74:75], 0, s[100:101]
	global_load_ushort v196, v[76:77], off
	global_load_ushort v200, v[74:75], off
	v_lshl_add_u64 v[76:77], v[76:77], 0, s[100:101]
	v_lshl_add_u64 v[74:75], v[74:75], 0, s[100:101]
	global_load_ushort v198, v[76:77], off
	global_load_ushort v203, v[74:75], off
	v_lshl_add_u64 v[76:77], v[76:77], 0, s[100:101]
	v_lshl_add_u64 v[74:75], v[74:75], 0, s[100:101]
	global_load_ushort v201, v[76:77], off
	global_load_ushort v205, v[74:75], off
	v_lshl_add_u64 v[76:77], v[76:77], 0, s[100:101]
	v_lshl_add_u64 v[74:75], v[74:75], 0, s[100:101]
	global_load_ushort v202, v[76:77], off
	global_load_ushort v207, v[74:75], off
	v_lshl_add_u64 v[76:77], v[76:77], 0, s[100:101]
	v_lshl_add_u64 v[74:75], v[74:75], 0, s[100:101]
	global_load_ushort v204, v[76:77], off
	global_load_ushort v208, v[74:75], off
	v_lshl_add_u64 v[74:75], v[74:75], 0, s[100:101]
	s_lshl_b32 s36, s36, 8
	global_load_ushort v209, v[74:75], off
	v_lshl_add_u64 v[76:77], v[76:77], 0, s[100:101]
	v_lshl_add_u64 v[70:71], v[92:93], 0, s[36:37]
	v_mad_i64_i32 v[72:73], s[8:9], v78, s90, v[70:71]
	global_load_ushort v206, v[76:77], off
	global_load_dword v210, v[72:73], off offset:1536
	v_lshl_add_u64 v[72:73], v[72:73], 0, s[100:101]
	global_load_dword v211, v[72:73], off offset:1536
	v_lshl_add_u64 v[72:73], v[72:73], 0, s[100:101]
	global_load_dword v212, v[72:73], off offset:1536
	v_lshl_add_u64 v[72:73], v[72:73], 0, s[100:101]
	global_load_dword v213, v[72:73], off offset:1536
	v_lshl_add_u64 v[72:73], v[72:73], 0, s[100:101]
	global_load_dword v214, v[72:73], off offset:1536
	v_lshl_add_u64 v[72:73], v[72:73], 0, s[100:101]
	global_load_dword v215, v[72:73], off offset:1536
	v_lshl_add_u64 v[72:73], v[72:73], 0, s[100:101]
	global_load_dword v216, v[72:73], off offset:1536
	v_lshl_add_u64 v[72:73], v[72:73], 0, s[100:101]
	global_load_dword v217, v[72:73], off offset:1536
	v_or_b32_e32 v0, s1, v145
	v_mul_u32_u24_e32 v0, 0x1400, v0
	v_add_u32_e32 v72, s36, v146
	v_lshl_add_u64 v[70:71], s[26:27], 0, v[0:1]
	v_ashrrev_i32_e32 v73, 31, v72
	v_lshl_add_u64 v[70:71], v[70:71], 0, v[72:73]
	global_load_dwordx2 v[142:143], v[70:71], off
	global_load_dwordx2 v[140:141], v[70:71], off offset:32
	global_load_dwordx2 v[138:139], v[70:71], off offset:64
	global_load_dwordx2 v[136:137], v[70:71], off offset:96
